# v19 with the 16 packed v_pk_add_f32 row-sum ops in the MLA MFMA stream split into scalar v_add_f32 pairs (packed fp32 beside MFMAs is an anti-lever)
# baseline (speedup 1.0000x reference)
.Lst_noK:
	v_mfma_f32_32x32x16_bf16 v[80:95], v[242:245], v[132:135], v[80:95]
	v_exp_f32_e32 v59, v59
	v_exp_f32_e32 v60, v60
	v_exp_f32_e32 v61, v61
	s_and_b32 s99, s71, 0x2000
	v_add_u32_e32 v176, s99, v192
	v_add_u32_e32 v177, s99, v193
	s_waitcnt vmcnt(0)
	ds_write_b64 v176, v[148:149] offset:32768
	ds_write_b64 v177, v[150:151]
	s_waitcnt lgkmcnt(5)
	v_mfma_f32_32x32x16_bf16 v[32:47], v[216:219], v[224:227], v[32:47]
	v_exp_f32_e32 v62, v62
	v_exp_f32_e32 v63, v63
	v_add_f32_e32 v64, v48, v64
	v_add_f32_e32 v65, v49, v65
	s_add_i32 s99, s73, 3
	s_cmp_ge_u32 s99, s70
	s_cbranch_scc1 .Lst_noKL
	s_lshl_b64 s[100:101], s[14:15], 11
	v_lshl_add_u64 v[174:175], v[166:167], 0, s[100:101]
	global_load_dwordx4 v[144:147], v[174:175], off
	s_and_saveexec_b64 s[100:101], s[6:7]
	s_cbranch_execz .Lst_noR
	s_lshl_b64 s[78:79], s[14:15], 6
	v_lshl_add_u64 v[174:175], v[164:165], 0, s[78:79]
	global_load_dwordx4 v[140:143], v[174:175], off

.Lst_noKL:
	s_waitcnt lgkmcnt(4)
	v_mfma_f32_32x32x16_bf16 v[16:31], v[220:223], v[224:227], v[16:31]
	v_cvt_pk_bf16_f32 v224, v56, v57
	v_cvt_pk_bf16_f32 v225, v58, v59
	v_cvt_pk_bf16_f32 v226, v60, v61
	v_cvt_pk_bf16_f32 v227, v62, v63
	v_add_f32_e32 v66, v50, v66
	v_add_f32_e32 v67, v51, v67
	s_cmp_ge_u32 s98, s70
	s_cbranch_scc1 .Lst_noVL
	s_sub_i32 s100, s14, 64
	s_mov_b32 s101, s15
	v_lshl_add_u64 v[174:175], s[100:101], 1, v[168:169]
	global_load_dwordx4 v[148:151], v[174:175], off
.Lst_noVL:
	s_mov_b32 s98, 1
	v_mfma_f32_32x32x16_bf16 v[96:111], v[246:249], v[136:139], v[96:111]
	v_add_f32_e32 v68, v52, v68
	v_add_f32_e32 v69, v53, v69
	v_add_f32_e32 v70, v54, v70
	v_add_f32_e32 v71, v55, v71
	v_add_f32_e32 v72, v56, v72
	v_add_f32_e32 v73, v57, v73
	v_mfma_f32_32x32x16_bf16 v[80:95], v[250:253], v[136:139], v[80:95]
	v_add_f32_e32 v74, v58, v74
	v_add_f32_e32 v75, v59, v75
	v_add_f32_e32 v76, v60, v76
	v_add_f32_e32 v77, v61, v77
	v_add_f32_e32 v78, v62, v78
	v_add_f32_e32 v79, v63, v79
	s_waitcnt lgkmcnt(3)
	v_mfma_f32_32x32x16_bf16 v[32:47], v[230:233], v[224:227], v[32:47]
	v_add_f32_e32 v0, v64, v0
	v_add_f32_e32 v1, v65, v1
	v_add_f32_e32 v2, v66, v2
	v_add_f32_e32 v3, v67, v3
	v_add_f32_e32 v4, v68, v4
	v_add_f32_e32 v5, v69, v5
	s_waitcnt lgkmcnt(2)
	v_mfma_f32_32x32x16_bf16 v[16:31], v[234:237], v[224:227], v[16:31]
	v_cmp_neq_f32_e32 vcc, 0, v229
	v_add_f32_e32 v6, v70, v6
	v_add_f32_e32 v7, v71, v7
	v_add_f32_e32 v8, v72, v8
	v_add_f32_e32 v9, v73, v9
	v_add_f32_e32 v10, v74, v10
	v_add_f32_e32 v11, v75, v11
	v_add_f32_e32 v12, v76, v12
	v_add_f32_e32 v13, v77, v13
	v_add_f32_e32 v14, v78, v14
	v_add_f32_e32 v15, v79, v15
	s_cbranch_vccz .LBB0_453
	v_sub_f32_e32 v111, v111, v229
	v_sub_f32_e32 v110, v110, v229
	v_sub_f32_e32 v109, v109, v229
	v_sub_f32_e32 v108, v108, v229
	v_sub_f32_e32 v107, v107, v229
	v_sub_f32_e32 v106, v106, v229
	v_sub_f32_e32 v105, v105, v229
	v_sub_f32_e32 v104, v104, v229
	v_sub_f32_e32 v103, v103, v229
	v_sub_f32_e32 v102, v102, v229
	v_sub_f32_e32 v101, v101, v229
	v_sub_f32_e32 v100, v100, v229
	v_sub_f32_e32 v99, v99, v229
	v_sub_f32_e32 v98, v98, v229
	v_sub_f32_e32 v97, v97, v229
	v_sub_f32_e32 v96, v96, v229
	v_sub_f32_e32 v95, v95, v229
	v_sub_f32_e32 v94, v94, v229
	v_sub_f32_e32 v93, v93, v229
	v_sub_f32_e32 v92, v92, v229
	v_sub_f32_e32 v91, v91, v229
	v_sub_f32_e32 v90, v90, v229
	v_sub_f32_e32 v89, v89, v229
	v_sub_f32_e32 v88, v88, v229
	v_sub_f32_e32 v87, v87, v229
	v_sub_f32_e32 v86, v86, v229
	v_sub_f32_e32 v85, v85, v229
	v_sub_f32_e32 v84, v84, v229
	v_sub_f32_e32 v83, v83, v229
	v_sub_f32_e32 v82, v82, v229
	v_sub_f32_e32 v81, v81, v229
	v_sub_f32_e32 v80, v80, v229

.Lsto_noK:
	v_mfma_f32_32x32x16_bf16 v[48:63], v[242:245], v[132:135], v[48:63]
	v_exp_f32_e32 v91, v91
	v_exp_f32_e32 v92, v92
	v_exp_f32_e32 v93, v93
	s_and_b32 s99, s71, 0x2000
	v_add_u32_e32 v176, s99, v192
	v_add_u32_e32 v177, s99, v193
	s_waitcnt vmcnt(0)
	ds_write_b64 v176, v[148:149] offset:32768
	ds_write_b64 v177, v[150:151]
	s_waitcnt lgkmcnt(5)
	v_mfma_f32_32x32x16_bf16 v[32:47], v[216:219], v[224:227], v[32:47]
	v_exp_f32_e32 v94, v94
	v_exp_f32_e32 v95, v95
	v_add_f32_e32 v96, v80, v96
	v_add_f32_e32 v97, v81, v97
	s_add_i32 s99, s73, 3
	s_cmp_ge_u32 s99, s70
	s_cbranch_scc1 .Lsto_noKL
	s_lshl_b64 s[100:101], s[14:15], 11
	v_lshl_add_u64 v[174:175], v[166:167], 0, s[100:101]
	global_load_dwordx4 v[144:147], v[174:175], off
	s_and_saveexec_b64 s[100:101], s[6:7]
	s_cbranch_execz .Lsto_noR
	s_lshl_b64 s[78:79], s[14:15], 6
	v_lshl_add_u64 v[174:175], v[164:165], 0, s[78:79]
	global_load_dwordx4 v[140:143], v[174:175], off

.Lsto_noKL:
	s_waitcnt lgkmcnt(4)
	v_mfma_f32_32x32x16_bf16 v[16:31], v[220:223], v[224:227], v[16:31]
	v_cvt_pk_bf16_f32 v224, v88, v89
	v_cvt_pk_bf16_f32 v225, v90, v91
	v_cvt_pk_bf16_f32 v226, v92, v93
	v_cvt_pk_bf16_f32 v227, v94, v95
	v_add_f32_e32 v98, v82, v98
	v_add_f32_e32 v99, v83, v99
	s_cmp_ge_u32 s98, s70
	s_cbranch_scc1 .Lsto_noVL
	s_sub_i32 s100, s14, 64
	s_mov_b32 s101, s15
	v_lshl_add_u64 v[174:175], s[100:101], 1, v[168:169]
	global_load_dwordx4 v[148:151], v[174:175], off
.Lsto_noVL:
	s_mov_b32 s98, 1
	v_mfma_f32_32x32x16_bf16 v[64:79], v[246:249], v[136:139], v[64:79]
	v_add_f32_e32 v100, v84, v100
	v_add_f32_e32 v101, v85, v101
	v_add_f32_e32 v102, v86, v102
	v_add_f32_e32 v103, v87, v103
	v_add_f32_e32 v104, v88, v104
	v_add_f32_e32 v105, v89, v105
	v_mfma_f32_32x32x16_bf16 v[48:63], v[250:253], v[136:139], v[48:63]
	v_add_f32_e32 v106, v90, v106
	v_add_f32_e32 v107, v91, v107
	v_add_f32_e32 v108, v92, v108
	v_add_f32_e32 v109, v93, v109
	v_add_f32_e32 v110, v94, v110
	v_add_f32_e32 v111, v95, v111
	s_waitcnt lgkmcnt(3)
	v_mfma_f32_32x32x16_bf16 v[32:47], v[230:233], v[224:227], v[32:47]
	v_add_f32_e32 v0, v96, v0
	v_add_f32_e32 v1, v97, v1
	v_add_f32_e32 v2, v98, v2
	v_add_f32_e32 v3, v99, v3
	v_add_f32_e32 v4, v100, v4
	v_add_f32_e32 v5, v101, v5
	s_waitcnt lgkmcnt(2)
	v_mfma_f32_32x32x16_bf16 v[16:31], v[234:237], v[224:227], v[16:31]
	v_cmp_neq_f32_e32 vcc, 0, v229
	v_add_f32_e32 v6, v102, v6
	v_add_f32_e32 v7, v103, v7
	v_add_f32_e32 v8, v104, v8
	v_add_f32_e32 v9, v105, v9
	v_add_f32_e32 v10, v106, v10
	v_add_f32_e32 v11, v107, v11
	v_add_f32_e32 v12, v108, v12
	v_add_f32_e32 v13, v109, v13
	v_add_f32_e32 v14, v110, v14
	v_add_f32_e32 v15, v111, v15
	s_cbranch_vccz .Lmo_453
	v_sub_f32_e32 v79, v79, v229
	v_sub_f32_e32 v78, v78, v229
	v_sub_f32_e32 v77, v77, v229
	v_sub_f32_e32 v76, v76, v229
	v_sub_f32_e32 v75, v75, v229
	v_sub_f32_e32 v74, v74, v229
	v_sub_f32_e32 v73, v73, v229
	v_sub_f32_e32 v72, v72, v229
	v_sub_f32_e32 v71, v71, v229
	v_sub_f32_e32 v70, v70, v229
	v_sub_f32_e32 v69, v69, v229
	v_sub_f32_e32 v68, v68, v229
	v_sub_f32_e32 v67, v67, v229
	v_sub_f32_e32 v66, v66, v229
	v_sub_f32_e32 v65, v65, v229
	v_sub_f32_e32 v64, v64, v229
	v_sub_f32_e32 v63, v63, v229
	v_sub_f32_e32 v62, v62, v229
	v_sub_f32_e32 v61, v61, v229
	v_sub_f32_e32 v60, v60, v229
	v_sub_f32_e32 v59, v59, v229
	v_sub_f32_e32 v58, v58, v229
	v_sub_f32_e32 v57, v57, v229
	v_sub_f32_e32 v56, v56, v229
	v_sub_f32_e32 v55, v55, v229
	v_sub_f32_e32 v54, v54, v229
	v_sub_f32_e32 v53, v53, v229
	v_sub_f32_e32 v52, v52, v229
	v_sub_f32_e32 v51, v51, v229
	v_sub_f32_e32 v50, v50, v229
	v_sub_f32_e32 v49, v49, v229
	v_sub_f32_e32 v48, v48, v229
